# FF2 owner epilogue: all partial-slot loads of a row group issued before one wait (was load-wait-add per partial)
# speedup vs baseline: 1.0023x; 1.0023x over previous
.LBB0_1423:
	v_ashrrev_i32_e32 v205, 31, v204
	v_lshlrev_b64 v[160:161], 12, v[204:205]
	v_lshl_add_u64 v[176:177], s[10:11], 0, v[160:161]
	v_lshl_add_u64 v[178:179], v[200:201], 2, v[176:177]
	global_load_dwordx4 v[164:167], v[178:179], off offset:16
	global_load_dwordx4 v[160:163], v[178:179], off
	s_cmp_eq_u32 s34, 2
	v_mov_b64_e32 v[174:175], v[126:127]
	v_mov_b64_e32 v[170:171], v[122:123]
	s_cselect_b64 s[88:89], -1, 0
	s_cmp_lg_u32 s34, 2
	v_mov_b64_e32 v[172:173], v[124:125]
	v_mov_b64_e32 v[168:169], v[120:121]
	s_cbranch_scc1 .LBB0_1428
	s_mov_b64 s[84:85], s[62:63]
	v_lshlrev_b32_e32 v180, 2, v194
	v_mov_b32_e32 v181, v185
	s_cmp_lt_i32 s30, 2
	v_lshl_add_u64 v[182:183], s[84:85], 0, v[180:181]
	flat_load_dwordx4 v[168:171], v[182:183]
	s_cbranch_scc1 .Lskw_0
	v_add_co_u32_e32 v182, vcc, 0x20000, v182
	s_nop 1
	v_addc_co_u32_e32 v183, vcc, 0, v183, vcc
	flat_load_dwordx4 v[206:209], v[182:183]
	s_cmp_lt_i32 s30, 3
	s_cbranch_scc1 .Lskw_0
	v_mov_b32_e32 v181, v185
	v_lshl_add_u64 v[180:181], s[84:85], 0, v[180:181]
	v_add_co_u32_e32 v180, vcc, 0x40000, v180
	s_nop 1
	v_addc_co_u32_e32 v181, vcc, 0, v181, vcc
	flat_load_dwordx4 v[180:183], v[180:181]
.Lskw_0:
	s_waitcnt vmcnt(0) lgkmcnt(0)
	v_lshlrev_b32_e32 v172, 16, v168
	v_and_b32_e32 v173, 0xffff0000, v168
	v_lshlrev_b32_e32 v168, 16, v169
	v_and_b32_e32 v169, 0xffff0000, v169
	v_lshlrev_b32_e32 v210, 16, v170
	v_and_b32_e32 v211, 0xffff0000, v170
	v_lshlrev_b32_e32 v170, 16, v171
	v_and_b32_e32 v171, 0xffff0000, v171
	v_pk_add_f32 v[174:175], v[126:127], v[168:169]
	v_pk_add_f32 v[172:173], v[124:125], v[172:173]
	v_pk_add_f32 v[170:171], v[122:123], v[170:171]
	v_pk_add_f32 v[168:169], v[120:121], v[210:211]
	s_cmp_lt_i32 s30, 2
	s_cbranch_scc1 .LBB0_1428
	v_lshlrev_b32_e32 v210, 16, v206
	v_and_b32_e32 v211, 0xffff0000, v206
	v_lshlrev_b32_e32 v206, 16, v207
	v_and_b32_e32 v207, 0xffff0000, v207
	v_pk_add_f32 v[174:175], v[174:175], v[206:207]
	v_pk_add_f32 v[172:173], v[172:173], v[210:211]
	v_lshlrev_b32_e32 v210, 16, v208
	v_and_b32_e32 v211, 0xffff0000, v208
	v_lshlrev_b32_e32 v206, 16, v209
	v_and_b32_e32 v207, 0xffff0000, v209
	v_pk_add_f32 v[170:171], v[170:171], v[206:207]
	v_pk_add_f32 v[168:169], v[168:169], v[210:211]
	s_cmp_lt_i32 s30, 3
	s_cbranch_scc1 .LBB0_1428
	v_lshlrev_b32_e32 v206, 16, v180
	v_and_b32_e32 v207, 0xffff0000, v180
	v_lshlrev_b32_e32 v180, 16, v181
	v_and_b32_e32 v181, 0xffff0000, v181
	v_pk_add_f32 v[174:175], v[174:175], v[180:181]
	v_lshlrev_b32_e32 v180, 16, v182
	v_and_b32_e32 v181, 0xffff0000, v182
	v_lshlrev_b32_e32 v182, 16, v183
	v_and_b32_e32 v183, 0xffff0000, v183
	v_pk_add_f32 v[172:173], v[172:173], v[206:207]
	v_pk_add_f32 v[170:171], v[170:171], v[182:183]
	v_pk_add_f32 v[168:169], v[168:169], v[180:181]

.LBB0_1430:
	v_lshl_add_u64 v[208:209], v[200:201], 2, v[176:177]
	global_load_dwordx4 v[168:171], v[208:209], off offset:528
	global_load_dwordx4 v[172:175], v[208:209], off offset:512
	v_cndmask_b32_e64 v176, 0, 1, s[88:89]
	v_cmp_ne_u32_e64 s[84:85], 1, v176
	v_mov_b64_e32 v[182:183], v[94:95]
	v_mov_b64_e32 v[178:179], v[90:91]
	s_andn2_b64 vcc, exec, s[88:89]
	v_mov_b64_e32 v[180:181], v[92:93]
	v_mov_b64_e32 v[176:177], v[88:89]
	s_cbranch_vccnz .LBB0_1435
	v_readlane_b32 s88, v242, 16
	v_readlane_b32 s89, v242, 17
	v_lshlrev_b32_e32 v210, 2, v194
	v_mov_b32_e32 v211, v185
	s_cmp_lt_i32 s30, 2
	v_lshl_add_u64 v[212:213], s[88:89], 0, v[210:211]
	flat_load_dwordx4 v[176:179], v[212:213]
	s_cbranch_scc1 .Lskw_1
	v_add_co_u32_e32 v212, vcc, 0x20000, v212
	s_nop 1
	v_addc_co_u32_e32 v213, vcc, 0, v213, vcc
	flat_load_dwordx4 v[236:239], v[212:213]
	s_cmp_lt_i32 s30, 3
	s_cbranch_scc1 .Lskw_1
	v_mov_b32_e32 v211, v185
	v_lshl_add_u64 v[210:211], s[88:89], 0, v[210:211]
	v_add_co_u32_e32 v210, vcc, 0x40000, v210
	s_nop 1
	v_addc_co_u32_e32 v211, vcc, 0, v211, vcc
	flat_load_dwordx4 v[210:213], v[210:211]
.Lskw_1:
	s_waitcnt vmcnt(0) lgkmcnt(0)
	v_lshlrev_b32_e32 v180, 16, v176
	v_and_b32_e32 v181, 0xffff0000, v176
	v_lshlrev_b32_e32 v176, 16, v177
	v_and_b32_e32 v177, 0xffff0000, v177
	v_lshlrev_b32_e32 v240, 16, v178
	v_and_b32_e32 v241, 0xffff0000, v178
	v_lshlrev_b32_e32 v178, 16, v179
	v_and_b32_e32 v179, 0xffff0000, v179
	v_pk_add_f32 v[182:183], v[94:95], v[176:177]
	v_pk_add_f32 v[180:181], v[92:93], v[180:181]
	v_pk_add_f32 v[178:179], v[90:91], v[178:179]
	v_pk_add_f32 v[176:177], v[88:89], v[240:241]
	s_cmp_lt_i32 s30, 2
	s_cbranch_scc1 .LBB0_1435
	v_lshlrev_b32_e32 v240, 16, v236
	v_and_b32_e32 v241, 0xffff0000, v236
	v_lshlrev_b32_e32 v236, 16, v237
	v_and_b32_e32 v237, 0xffff0000, v237
	v_pk_add_f32 v[182:183], v[182:183], v[236:237]
	v_pk_add_f32 v[180:181], v[180:181], v[240:241]
	v_lshlrev_b32_e32 v240, 16, v238
	v_and_b32_e32 v241, 0xffff0000, v238
	v_lshlrev_b32_e32 v236, 16, v239
	v_and_b32_e32 v237, 0xffff0000, v239
	v_pk_add_f32 v[178:179], v[178:179], v[236:237]
	v_pk_add_f32 v[176:177], v[176:177], v[240:241]
	s_cmp_lt_i32 s30, 3
	s_cbranch_scc1 .LBB0_1435
	v_lshlrev_b32_e32 v236, 16, v210
	v_and_b32_e32 v237, 0xffff0000, v210
	v_lshlrev_b32_e32 v210, 16, v211
	v_and_b32_e32 v211, 0xffff0000, v211
	v_pk_add_f32 v[182:183], v[182:183], v[210:211]
	v_lshlrev_b32_e32 v210, 16, v212
	v_and_b32_e32 v211, 0xffff0000, v212
	v_lshlrev_b32_e32 v212, 16, v213
	v_and_b32_e32 v213, 0xffff0000, v213
	v_pk_add_f32 v[180:181], v[180:181], v[236:237]
	v_pk_add_f32 v[178:179], v[178:179], v[212:213]
	v_pk_add_f32 v[176:177], v[176:177], v[210:211]

.LBB0_1442:
	v_ashrrev_i32_e32 v205, 31, v204
	v_lshlrev_b64 v[160:161], 12, v[204:205]
	v_lshl_add_u64 v[176:177], s[10:11], 0, v[160:161]
	v_lshl_add_u64 v[178:179], v[200:201], 2, v[176:177]
	global_load_dwordx4 v[164:167], v[178:179], off offset:16
	global_load_dwordx4 v[160:163], v[178:179], off
	v_mov_b64_e32 v[174:175], v[118:119]
	v_mov_b64_e32 v[170:171], v[114:115]
	s_and_b64 vcc, exec, s[84:85]
	v_mov_b64_e32 v[172:173], v[116:117]
	v_mov_b64_e32 v[168:169], v[112:113]
	s_cbranch_vccnz .LBB0_1447
	v_readlane_b32 s88, v242, 18
	v_readlane_b32 s89, v242, 19
	v_lshlrev_b32_e32 v180, 2, v194
	v_mov_b32_e32 v181, v185
	s_cmp_lt_i32 s30, 2
	v_lshl_add_u64 v[182:183], s[88:89], 0, v[180:181]
	flat_load_dwordx4 v[168:171], v[182:183]
	s_cbranch_scc1 .Lskw_2
	v_add_co_u32_e32 v182, vcc, 0x20000, v182
	s_nop 1
	v_addc_co_u32_e32 v183, vcc, 0, v183, vcc
	flat_load_dwordx4 v[206:209], v[182:183]
	s_cmp_lt_i32 s30, 3
	s_cbranch_scc1 .Lskw_2
	v_mov_b32_e32 v181, v185
	v_lshl_add_u64 v[180:181], s[88:89], 0, v[180:181]
	v_add_co_u32_e32 v180, vcc, 0x40000, v180
	s_nop 1
	v_addc_co_u32_e32 v181, vcc, 0, v181, vcc
	flat_load_dwordx4 v[180:183], v[180:181]
.Lskw_2:
	s_waitcnt vmcnt(0) lgkmcnt(0)
	v_lshlrev_b32_e32 v172, 16, v168
	v_and_b32_e32 v173, 0xffff0000, v168
	v_lshlrev_b32_e32 v168, 16, v169
	v_and_b32_e32 v169, 0xffff0000, v169
	v_lshlrev_b32_e32 v210, 16, v170
	v_and_b32_e32 v211, 0xffff0000, v170
	v_lshlrev_b32_e32 v170, 16, v171
	v_and_b32_e32 v171, 0xffff0000, v171
	v_pk_add_f32 v[174:175], v[118:119], v[168:169]
	v_pk_add_f32 v[172:173], v[116:117], v[172:173]
	v_pk_add_f32 v[170:171], v[114:115], v[170:171]
	v_pk_add_f32 v[168:169], v[112:113], v[210:211]
	s_cmp_lt_i32 s30, 2
	s_cbranch_scc1 .LBB0_1447
	v_lshlrev_b32_e32 v210, 16, v206
	v_and_b32_e32 v211, 0xffff0000, v206
	v_lshlrev_b32_e32 v206, 16, v207
	v_and_b32_e32 v207, 0xffff0000, v207
	v_pk_add_f32 v[174:175], v[174:175], v[206:207]
	v_pk_add_f32 v[172:173], v[172:173], v[210:211]
	v_lshlrev_b32_e32 v210, 16, v208
	v_and_b32_e32 v211, 0xffff0000, v208
	v_lshlrev_b32_e32 v206, 16, v209
	v_and_b32_e32 v207, 0xffff0000, v209
	v_pk_add_f32 v[170:171], v[170:171], v[206:207]
	v_pk_add_f32 v[168:169], v[168:169], v[210:211]
	s_cmp_lt_i32 s30, 3
	s_cbranch_scc1 .LBB0_1447
	v_lshlrev_b32_e32 v206, 16, v180
	v_and_b32_e32 v207, 0xffff0000, v180
	v_lshlrev_b32_e32 v180, 16, v181
	v_and_b32_e32 v181, 0xffff0000, v181
	v_pk_add_f32 v[174:175], v[174:175], v[180:181]
	v_lshlrev_b32_e32 v180, 16, v182
	v_and_b32_e32 v181, 0xffff0000, v182
	v_lshlrev_b32_e32 v182, 16, v183
	v_and_b32_e32 v183, 0xffff0000, v183
	v_pk_add_f32 v[172:173], v[172:173], v[206:207]
	v_pk_add_f32 v[170:171], v[170:171], v[182:183]
	v_pk_add_f32 v[168:169], v[168:169], v[180:181]

.LBB0_1449:
	v_lshl_add_u64 v[208:209], v[200:201], 2, v[176:177]
	global_load_dwordx4 v[168:171], v[208:209], off offset:528
	global_load_dwordx4 v[172:175], v[208:209], off offset:512
	v_mov_b64_e32 v[182:183], v[86:87]
	v_mov_b64_e32 v[178:179], v[82:83]
	s_and_b64 vcc, exec, s[84:85]
	v_mov_b64_e32 v[180:181], v[84:85]
	v_mov_b64_e32 v[176:177], v[80:81]
	s_cbranch_vccnz .LBB0_1454
	v_readlane_b32 s88, v242, 20
	v_readlane_b32 s89, v242, 21
	v_lshlrev_b32_e32 v210, 2, v194
	v_mov_b32_e32 v211, v185
	s_cmp_lt_i32 s30, 2
	v_lshl_add_u64 v[212:213], s[88:89], 0, v[210:211]
	flat_load_dwordx4 v[176:179], v[212:213]
	s_cbranch_scc1 .Lskw_3
	v_add_co_u32_e32 v212, vcc, 0x20000, v212
	s_nop 1
	v_addc_co_u32_e32 v213, vcc, 0, v213, vcc
	flat_load_dwordx4 v[238:241], v[212:213]
	s_cmp_lt_i32 s30, 3
	s_cbranch_scc1 .Lskw_3
	v_mov_b32_e32 v211, v185
	v_lshl_add_u64 v[210:211], s[88:89], 0, v[210:211]
	v_add_co_u32_e32 v210, vcc, 0x40000, v210
	s_nop 1
	v_addc_co_u32_e32 v211, vcc, 0, v211, vcc
	flat_load_dwordx4 v[210:213], v[210:211]
.Lskw_3:
	s_waitcnt vmcnt(0) lgkmcnt(0)
	v_lshlrev_b32_e32 v180, 16, v176
	v_and_b32_e32 v181, 0xffff0000, v176
	v_lshlrev_b32_e32 v176, 16, v177
	v_and_b32_e32 v177, 0xffff0000, v177
	v_lshlrev_b32_e32 v203, 16, v178
	v_and_b32_e32 v205, 0xffff0000, v178
	v_lshlrev_b32_e32 v178, 16, v179
	v_and_b32_e32 v179, 0xffff0000, v179
	v_pk_add_f32 v[182:183], v[86:87], v[176:177]
	v_pk_add_f32 v[180:181], v[84:85], v[180:181]
	v_pk_add_f32 v[178:179], v[82:83], v[178:179]
	v_add_f32_e32 v176, v80, v203
	v_add_f32_e32 v177, v81, v205
	s_cmp_lt_i32 s30, 2
	s_cbranch_scc1 .LBB0_1454
	v_lshlrev_b32_e32 v203, 16, v238
	v_and_b32_e32 v205, 0xffff0000, v238
	v_lshlrev_b32_e32 v238, 16, v239
	v_and_b32_e32 v239, 0xffff0000, v239
	v_pk_add_f32 v[182:183], v[182:183], v[238:239]
	v_add_f32_e32 v180, v180, v203
	v_add_f32_e32 v181, v181, v205
	v_lshlrev_b32_e32 v203, 16, v240
	v_and_b32_e32 v205, 0xffff0000, v240
	v_lshlrev_b32_e32 v238, 16, v241
	v_and_b32_e32 v239, 0xffff0000, v241
	v_pk_add_f32 v[178:179], v[178:179], v[238:239]
	v_add_f32_e32 v176, v176, v203
	v_add_f32_e32 v177, v177, v205
	s_cmp_lt_i32 s30, 3
	s_cbranch_scc1 .LBB0_1454
	v_lshlrev_b32_e32 v238, 16, v210
	v_and_b32_e32 v239, 0xffff0000, v210
	v_lshlrev_b32_e32 v210, 16, v211
	v_and_b32_e32 v211, 0xffff0000, v211
	v_pk_add_f32 v[182:183], v[182:183], v[210:211]
	v_lshlrev_b32_e32 v210, 16, v212
	v_and_b32_e32 v211, 0xffff0000, v212
	v_lshlrev_b32_e32 v212, 16, v213
	v_and_b32_e32 v213, 0xffff0000, v213
	v_pk_add_f32 v[180:181], v[180:181], v[238:239]
	v_pk_add_f32 v[178:179], v[178:179], v[212:213]
	v_pk_add_f32 v[176:177], v[176:177], v[210:211]

.LBB0_1461:
	v_ashrrev_i32_e32 v205, 31, v204
	v_lshlrev_b64 v[160:161], 12, v[204:205]
	v_lshl_add_u64 v[176:177], s[10:11], 0, v[160:161]
	v_lshl_add_u64 v[178:179], v[200:201], 2, v[176:177]
	global_load_dwordx4 v[164:167], v[178:179], off offset:16
	global_load_dwordx4 v[160:163], v[178:179], off
	v_mov_b64_e32 v[174:175], v[110:111]
	v_mov_b64_e32 v[170:171], v[106:107]
	s_and_b64 vcc, exec, s[84:85]
	v_mov_b64_e32 v[172:173], v[108:109]
	v_mov_b64_e32 v[168:169], v[104:105]
	s_cbranch_vccnz .LBB0_1466
	v_readlane_b32 s88, v242, 22
	v_readlane_b32 s89, v242, 23
	v_lshlrev_b32_e32 v180, 2, v194
	v_mov_b32_e32 v181, v185
	s_cmp_lt_i32 s30, 2
	v_lshl_add_u64 v[182:183], s[88:89], 0, v[180:181]
	flat_load_dwordx4 v[168:171], v[182:183]
	s_cbranch_scc1 .Lskw_4
	v_add_co_u32_e32 v182, vcc, 0x20000, v182
	s_nop 1
	v_addc_co_u32_e32 v183, vcc, 0, v183, vcc
	flat_load_dwordx4 v[206:209], v[182:183]
	s_cmp_lt_i32 s30, 3
	s_cbranch_scc1 .Lskw_4
	v_mov_b32_e32 v181, v185
	v_lshl_add_u64 v[180:181], s[88:89], 0, v[180:181]
	v_add_co_u32_e32 v180, vcc, 0x40000, v180
	s_nop 1
	v_addc_co_u32_e32 v181, vcc, 0, v181, vcc
	flat_load_dwordx4 v[180:183], v[180:181]
.Lskw_4:
	s_waitcnt vmcnt(0) lgkmcnt(0)
	v_lshlrev_b32_e32 v172, 16, v168
	v_and_b32_e32 v173, 0xffff0000, v168
	v_lshlrev_b32_e32 v168, 16, v169
	v_and_b32_e32 v169, 0xffff0000, v169
	v_lshlrev_b32_e32 v210, 16, v170
	v_and_b32_e32 v211, 0xffff0000, v170
	v_lshlrev_b32_e32 v170, 16, v171
	v_and_b32_e32 v171, 0xffff0000, v171
	v_pk_add_f32 v[174:175], v[110:111], v[168:169]
	v_pk_add_f32 v[172:173], v[108:109], v[172:173]
	v_pk_add_f32 v[170:171], v[106:107], v[170:171]
	v_pk_add_f32 v[168:169], v[104:105], v[210:211]
	s_cmp_lt_i32 s30, 2
	s_cbranch_scc1 .LBB0_1466
	v_lshlrev_b32_e32 v210, 16, v206
	v_and_b32_e32 v211, 0xffff0000, v206
	v_lshlrev_b32_e32 v206, 16, v207
	v_and_b32_e32 v207, 0xffff0000, v207
	v_pk_add_f32 v[174:175], v[174:175], v[206:207]
	v_pk_add_f32 v[172:173], v[172:173], v[210:211]
	v_lshlrev_b32_e32 v210, 16, v208
	v_and_b32_e32 v211, 0xffff0000, v208
	v_lshlrev_b32_e32 v206, 16, v209
	v_and_b32_e32 v207, 0xffff0000, v209
	v_pk_add_f32 v[170:171], v[170:171], v[206:207]
	v_pk_add_f32 v[168:169], v[168:169], v[210:211]
	s_cmp_lt_i32 s30, 3
	s_cbranch_scc1 .LBB0_1466
	v_lshlrev_b32_e32 v206, 16, v180
	v_and_b32_e32 v207, 0xffff0000, v180
	v_lshlrev_b32_e32 v180, 16, v181
	v_and_b32_e32 v181, 0xffff0000, v181
	v_pk_add_f32 v[174:175], v[174:175], v[180:181]
	v_lshlrev_b32_e32 v180, 16, v182
	v_and_b32_e32 v181, 0xffff0000, v182
	v_lshlrev_b32_e32 v182, 16, v183
	v_and_b32_e32 v183, 0xffff0000, v183
	v_pk_add_f32 v[172:173], v[172:173], v[206:207]
	v_pk_add_f32 v[170:171], v[170:171], v[182:183]
	v_pk_add_f32 v[168:169], v[168:169], v[180:181]

.LBB0_1468:
	v_lshl_add_u64 v[208:209], v[200:201], 2, v[176:177]
	global_load_dwordx4 v[168:171], v[208:209], off offset:528
	global_load_dwordx4 v[172:175], v[208:209], off offset:512
	v_mov_b64_e32 v[182:183], v[78:79]
	v_mov_b64_e32 v[178:179], v[74:75]
	s_and_b64 vcc, exec, s[84:85]
	v_mov_b64_e32 v[180:181], v[76:77]
	v_mov_b64_e32 v[176:177], v[72:73]
	s_cbranch_vccnz .LBB0_1473
	v_readlane_b32 s88, v242, 24
	v_readlane_b32 s89, v242, 25
	v_lshlrev_b32_e32 v210, 2, v194
	v_mov_b32_e32 v211, v185
	s_cmp_lt_i32 s30, 2
	v_lshl_add_u64 v[212:213], s[88:89], 0, v[210:211]
	flat_load_dwordx4 v[176:179], v[212:213]
	s_cbranch_scc1 .Lskw_5
	v_add_co_u32_e32 v212, vcc, 0x20000, v212
	s_nop 1
	v_addc_co_u32_e32 v213, vcc, 0, v213, vcc
	flat_load_dwordx4 v[238:241], v[212:213]
	s_cmp_lt_i32 s30, 3
	s_cbranch_scc1 .Lskw_5
	v_mov_b32_e32 v211, v185
	v_lshl_add_u64 v[210:211], s[88:89], 0, v[210:211]
	v_add_co_u32_e32 v210, vcc, 0x40000, v210
	s_nop 1
	v_addc_co_u32_e32 v211, vcc, 0, v211, vcc
	flat_load_dwordx4 v[210:213], v[210:211]
.Lskw_5:
	s_waitcnt vmcnt(0) lgkmcnt(0)
	v_lshlrev_b32_e32 v180, 16, v176
	v_and_b32_e32 v181, 0xffff0000, v176
	v_lshlrev_b32_e32 v176, 16, v177
	v_and_b32_e32 v177, 0xffff0000, v177
	v_lshlrev_b32_e32 v203, 16, v178
	v_and_b32_e32 v205, 0xffff0000, v178
	v_lshlrev_b32_e32 v178, 16, v179
	v_and_b32_e32 v179, 0xffff0000, v179
	v_pk_add_f32 v[182:183], v[78:79], v[176:177]
	v_pk_add_f32 v[180:181], v[76:77], v[180:181]
	v_pk_add_f32 v[178:179], v[74:75], v[178:179]
	v_add_f32_e32 v176, v72, v203
	v_add_f32_e32 v177, v73, v205
	s_cmp_lt_i32 s30, 2
	s_cbranch_scc1 .LBB0_1473
	v_lshlrev_b32_e32 v203, 16, v238
	v_and_b32_e32 v205, 0xffff0000, v238
	v_lshlrev_b32_e32 v238, 16, v239
	v_and_b32_e32 v239, 0xffff0000, v239
	v_pk_add_f32 v[182:183], v[182:183], v[238:239]
	v_add_f32_e32 v180, v180, v203
	v_add_f32_e32 v181, v181, v205
	v_lshlrev_b32_e32 v203, 16, v240
	v_and_b32_e32 v205, 0xffff0000, v240
	v_lshlrev_b32_e32 v238, 16, v241
	v_and_b32_e32 v239, 0xffff0000, v241
	v_pk_add_f32 v[178:179], v[178:179], v[238:239]
	v_add_f32_e32 v176, v176, v203
	v_add_f32_e32 v177, v177, v205
	s_cmp_lt_i32 s30, 3
	s_cbranch_scc1 .LBB0_1473
	v_lshlrev_b32_e32 v238, 16, v210
	v_and_b32_e32 v239, 0xffff0000, v210
	v_lshlrev_b32_e32 v210, 16, v211
	v_and_b32_e32 v211, 0xffff0000, v211
	v_pk_add_f32 v[182:183], v[182:183], v[210:211]
	v_lshlrev_b32_e32 v210, 16, v212
	v_and_b32_e32 v211, 0xffff0000, v212
	v_lshlrev_b32_e32 v212, 16, v213
	v_and_b32_e32 v213, 0xffff0000, v213
	v_pk_add_f32 v[180:181], v[180:181], v[238:239]
	v_pk_add_f32 v[178:179], v[178:179], v[212:213]
	v_pk_add_f32 v[176:177], v[176:177], v[210:211]

.LBB0_1480:
	v_ashrrev_i32_e32 v205, 31, v204
	v_lshlrev_b64 v[160:161], 12, v[204:205]
	v_lshl_add_u64 v[176:177], s[10:11], 0, v[160:161]
	v_lshl_add_u64 v[178:179], v[200:201], 2, v[176:177]
	global_load_dwordx4 v[164:167], v[178:179], off offset:16
	global_load_dwordx4 v[160:163], v[178:179], off
	v_mov_b64_e32 v[174:175], v[102:103]
	v_mov_b64_e32 v[170:171], v[98:99]
	s_and_b64 vcc, exec, s[84:85]
	v_mov_b64_e32 v[172:173], v[100:101]
	v_mov_b64_e32 v[168:169], v[96:97]
	s_cbranch_vccnz .LBB0_1485
	v_readlane_b32 s88, v242, 26
	v_readlane_b32 s89, v242, 27
	v_lshlrev_b32_e32 v180, 2, v194
	v_mov_b32_e32 v181, v185
	s_cmp_lt_i32 s30, 2
	v_lshl_add_u64 v[182:183], s[88:89], 0, v[180:181]
	flat_load_dwordx4 v[168:171], v[182:183]
	s_cbranch_scc1 .Lskw_6
	v_add_co_u32_e32 v182, vcc, 0x20000, v182
	s_nop 1
	v_addc_co_u32_e32 v183, vcc, 0, v183, vcc
	flat_load_dwordx4 v[206:209], v[182:183]
	s_cmp_lt_i32 s30, 3
	s_cbranch_scc1 .Lskw_6
	v_mov_b32_e32 v181, v185
	v_lshl_add_u64 v[180:181], s[88:89], 0, v[180:181]
	v_add_co_u32_e32 v180, vcc, 0x40000, v180
	s_nop 1
	v_addc_co_u32_e32 v181, vcc, 0, v181, vcc
	flat_load_dwordx4 v[180:183], v[180:181]
.Lskw_6:
	s_waitcnt vmcnt(0) lgkmcnt(0)
	v_lshlrev_b32_e32 v172, 16, v168
	v_and_b32_e32 v173, 0xffff0000, v168
	v_lshlrev_b32_e32 v168, 16, v169
	v_and_b32_e32 v169, 0xffff0000, v169
	v_lshlrev_b32_e32 v210, 16, v170
	v_and_b32_e32 v211, 0xffff0000, v170
	v_lshlrev_b32_e32 v170, 16, v171
	v_and_b32_e32 v171, 0xffff0000, v171
	v_pk_add_f32 v[174:175], v[102:103], v[168:169]
	v_pk_add_f32 v[172:173], v[100:101], v[172:173]
	v_pk_add_f32 v[170:171], v[98:99], v[170:171]
	v_pk_add_f32 v[168:169], v[96:97], v[210:211]
	s_cmp_lt_i32 s30, 2
	s_cbranch_scc1 .LBB0_1485
	v_lshlrev_b32_e32 v210, 16, v206
	v_and_b32_e32 v211, 0xffff0000, v206
	v_lshlrev_b32_e32 v206, 16, v207
	v_and_b32_e32 v207, 0xffff0000, v207
	v_pk_add_f32 v[174:175], v[174:175], v[206:207]
	v_pk_add_f32 v[172:173], v[172:173], v[210:211]
	v_lshlrev_b32_e32 v210, 16, v208
	v_and_b32_e32 v211, 0xffff0000, v208
	v_lshlrev_b32_e32 v206, 16, v209
	v_and_b32_e32 v207, 0xffff0000, v209
	v_pk_add_f32 v[170:171], v[170:171], v[206:207]
	v_pk_add_f32 v[168:169], v[168:169], v[210:211]
	s_cmp_lt_i32 s30, 3
	s_cbranch_scc1 .LBB0_1485
	v_lshlrev_b32_e32 v206, 16, v180
	v_and_b32_e32 v207, 0xffff0000, v180
	v_lshlrev_b32_e32 v180, 16, v181
	v_and_b32_e32 v181, 0xffff0000, v181
	v_pk_add_f32 v[174:175], v[174:175], v[180:181]
	v_lshlrev_b32_e32 v180, 16, v182
	v_and_b32_e32 v181, 0xffff0000, v182
	v_lshlrev_b32_e32 v182, 16, v183
	v_and_b32_e32 v183, 0xffff0000, v183
	v_pk_add_f32 v[172:173], v[172:173], v[206:207]
	v_pk_add_f32 v[170:171], v[170:171], v[182:183]
	v_pk_add_f32 v[168:169], v[168:169], v[180:181]

.LBB0_1487:
	v_lshl_add_u64 v[208:209], v[200:201], 2, v[176:177]
	global_load_dwordx4 v[168:171], v[208:209], off offset:528
	global_load_dwordx4 v[172:175], v[208:209], off offset:512
	v_mov_b64_e32 v[182:183], v[70:71]
	v_mov_b64_e32 v[178:179], v[66:67]
	s_and_b64 vcc, exec, s[84:85]
	v_mov_b64_e32 v[180:181], v[68:69]
	v_mov_b64_e32 v[176:177], v[64:65]
	s_cbranch_vccnz .LBB0_1492
	v_readlane_b32 s88, v242, 28
	v_readlane_b32 s89, v242, 29
	v_lshlrev_b32_e32 v210, 2, v194
	v_mov_b32_e32 v211, v185
	s_cmp_lt_i32 s30, 2
	v_lshl_add_u64 v[212:213], s[88:89], 0, v[210:211]
	flat_load_dwordx4 v[176:179], v[212:213]
	s_cbranch_scc1 .Lskw_7
	v_add_co_u32_e32 v212, vcc, 0x20000, v212
	s_nop 1
	v_addc_co_u32_e32 v213, vcc, 0, v213, vcc
	flat_load_dwordx4 v[238:241], v[212:213]
	s_cmp_lt_i32 s30, 3
	s_cbranch_scc1 .Lskw_7
	v_mov_b32_e32 v211, v185
	v_lshl_add_u64 v[210:211], s[88:89], 0, v[210:211]
	v_add_co_u32_e32 v210, vcc, 0x40000, v210
	s_nop 1
	v_addc_co_u32_e32 v211, vcc, 0, v211, vcc
	flat_load_dwordx4 v[210:213], v[210:211]
.Lskw_7:
	s_waitcnt vmcnt(0) lgkmcnt(0)
	v_lshlrev_b32_e32 v180, 16, v176
	v_and_b32_e32 v181, 0xffff0000, v176
	v_lshlrev_b32_e32 v176, 16, v177
	v_and_b32_e32 v177, 0xffff0000, v177
	v_lshlrev_b32_e32 v203, 16, v178
	v_and_b32_e32 v205, 0xffff0000, v178
	v_lshlrev_b32_e32 v178, 16, v179
	v_and_b32_e32 v179, 0xffff0000, v179
	v_pk_add_f32 v[182:183], v[70:71], v[176:177]
	v_pk_add_f32 v[180:181], v[68:69], v[180:181]
	v_pk_add_f32 v[178:179], v[66:67], v[178:179]
	v_add_f32_e32 v176, v64, v203
	v_add_f32_e32 v177, v65, v205
	s_cmp_lt_i32 s30, 2
	s_cbranch_scc1 .LBB0_1492
	v_lshlrev_b32_e32 v203, 16, v238
	v_and_b32_e32 v205, 0xffff0000, v238
	v_lshlrev_b32_e32 v238, 16, v239
	v_and_b32_e32 v239, 0xffff0000, v239
	v_pk_add_f32 v[182:183], v[182:183], v[238:239]
	v_add_f32_e32 v180, v180, v203
	v_add_f32_e32 v181, v181, v205
	v_lshlrev_b32_e32 v203, 16, v240
	v_and_b32_e32 v205, 0xffff0000, v240
	v_lshlrev_b32_e32 v238, 16, v241
	v_and_b32_e32 v239, 0xffff0000, v241
	v_pk_add_f32 v[178:179], v[178:179], v[238:239]
	v_add_f32_e32 v176, v176, v203
	v_add_f32_e32 v177, v177, v205
	s_cmp_lt_i32 s30, 3
	s_cbranch_scc1 .LBB0_1492
	v_lshlrev_b32_e32 v238, 16, v210
	v_and_b32_e32 v239, 0xffff0000, v210
	v_lshlrev_b32_e32 v210, 16, v211
	v_and_b32_e32 v211, 0xffff0000, v211
	v_pk_add_f32 v[182:183], v[182:183], v[210:211]
	v_lshlrev_b32_e32 v210, 16, v212
	v_and_b32_e32 v211, 0xffff0000, v212
	v_lshlrev_b32_e32 v212, 16, v213
	v_and_b32_e32 v213, 0xffff0000, v213
	v_pk_add_f32 v[180:181], v[180:181], v[238:239]
	v_pk_add_f32 v[178:179], v[178:179], v[212:213]
	v_pk_add_f32 v[176:177], v[176:177], v[210:211]

.LBB0_1499:
	v_ashrrev_i32_e32 v205, 31, v204
	v_lshlrev_b64 v[160:161], 12, v[204:205]
	v_lshl_add_u64 v[176:177], s[10:11], 0, v[160:161]
	v_lshl_add_u64 v[178:179], v[200:201], 2, v[176:177]
	global_load_dwordx4 v[164:167], v[178:179], off offset:16
	global_load_dwordx4 v[160:163], v[178:179], off
	v_mov_b64_e32 v[174:175], v[62:63]
	v_mov_b64_e32 v[170:171], v[58:59]
	s_and_b64 vcc, exec, s[84:85]
	v_mov_b64_e32 v[172:173], v[60:61]
	v_mov_b64_e32 v[168:169], v[56:57]
	s_cbranch_vccnz .LBB0_1504
	v_readlane_b32 s88, v242, 30
	v_readlane_b32 s89, v242, 31
	v_lshlrev_b32_e32 v180, 2, v194
	v_mov_b32_e32 v181, v185
	s_cmp_lt_i32 s30, 2
	v_lshl_add_u64 v[182:183], s[88:89], 0, v[180:181]
	flat_load_dwordx4 v[168:171], v[182:183]
	s_cbranch_scc1 .Lskw_8
	v_add_co_u32_e32 v182, vcc, 0x20000, v182
	s_nop 1
	v_addc_co_u32_e32 v183, vcc, 0, v183, vcc
	flat_load_dwordx4 v[206:209], v[182:183]
	s_cmp_lt_i32 s30, 3
	s_cbranch_scc1 .Lskw_8
	v_mov_b32_e32 v181, v185
	v_lshl_add_u64 v[180:181], s[88:89], 0, v[180:181]
	v_add_co_u32_e32 v180, vcc, 0x40000, v180
	s_nop 1
	v_addc_co_u32_e32 v181, vcc, 0, v181, vcc
	flat_load_dwordx4 v[180:183], v[180:181]
.Lskw_8:
	s_waitcnt vmcnt(0) lgkmcnt(0)
	v_lshlrev_b32_e32 v172, 16, v168
	v_and_b32_e32 v173, 0xffff0000, v168
	v_lshlrev_b32_e32 v168, 16, v169
	v_and_b32_e32 v169, 0xffff0000, v169
	v_lshlrev_b32_e32 v210, 16, v170
	v_and_b32_e32 v211, 0xffff0000, v170
	v_lshlrev_b32_e32 v170, 16, v171
	v_and_b32_e32 v171, 0xffff0000, v171
	v_pk_add_f32 v[174:175], v[62:63], v[168:169]
	v_pk_add_f32 v[172:173], v[60:61], v[172:173]
	v_pk_add_f32 v[170:171], v[58:59], v[170:171]
	v_pk_add_f32 v[168:169], v[56:57], v[210:211]
	s_cmp_lt_i32 s30, 2
	s_cbranch_scc1 .LBB0_1504
	v_lshlrev_b32_e32 v210, 16, v206
	v_and_b32_e32 v211, 0xffff0000, v206
	v_lshlrev_b32_e32 v206, 16, v207
	v_and_b32_e32 v207, 0xffff0000, v207
	v_pk_add_f32 v[174:175], v[174:175], v[206:207]
	v_pk_add_f32 v[172:173], v[172:173], v[210:211]
	v_lshlrev_b32_e32 v210, 16, v208
	v_and_b32_e32 v211, 0xffff0000, v208
	v_lshlrev_b32_e32 v206, 16, v209
	v_and_b32_e32 v207, 0xffff0000, v209
	v_pk_add_f32 v[170:171], v[170:171], v[206:207]
	v_pk_add_f32 v[168:169], v[168:169], v[210:211]
	s_cmp_lt_i32 s30, 3
	s_cbranch_scc1 .LBB0_1504
	v_lshlrev_b32_e32 v206, 16, v180
	v_and_b32_e32 v207, 0xffff0000, v180
	v_lshlrev_b32_e32 v180, 16, v181
	v_and_b32_e32 v181, 0xffff0000, v181
	v_pk_add_f32 v[174:175], v[174:175], v[180:181]
	v_lshlrev_b32_e32 v180, 16, v182
	v_and_b32_e32 v181, 0xffff0000, v182
	v_lshlrev_b32_e32 v182, 16, v183
	v_and_b32_e32 v183, 0xffff0000, v183
	v_pk_add_f32 v[172:173], v[172:173], v[206:207]
	v_pk_add_f32 v[170:171], v[170:171], v[182:183]
	v_pk_add_f32 v[168:169], v[168:169], v[180:181]

.LBB0_1506:
	v_lshl_add_u64 v[208:209], v[200:201], 2, v[176:177]
	global_load_dwordx4 v[168:171], v[208:209], off offset:528
	global_load_dwordx4 v[172:175], v[208:209], off offset:512
	v_mov_b64_e32 v[182:183], v[30:31]
	v_mov_b64_e32 v[178:179], v[26:27]
	s_and_b64 vcc, exec, s[84:85]
	v_mov_b64_e32 v[180:181], v[28:29]
	v_mov_b64_e32 v[176:177], v[24:25]
	s_cbranch_vccnz .LBB0_1511
	v_readlane_b32 s88, v242, 32
	v_readlane_b32 s89, v242, 33
	v_lshlrev_b32_e32 v210, 2, v194
	v_mov_b32_e32 v211, v185
	s_cmp_lt_i32 s30, 2
	v_lshl_add_u64 v[212:213], s[88:89], 0, v[210:211]
	flat_load_dwordx4 v[176:179], v[212:213]
	s_cbranch_scc1 .Lskw_9
	v_add_co_u32_e32 v212, vcc, 0x20000, v212
	s_nop 1
	v_addc_co_u32_e32 v213, vcc, 0, v213, vcc
	flat_load_dwordx4 v[238:241], v[212:213]
	s_cmp_lt_i32 s30, 3
	s_cbranch_scc1 .Lskw_9
	v_mov_b32_e32 v211, v185
	v_lshl_add_u64 v[210:211], s[88:89], 0, v[210:211]
	v_add_co_u32_e32 v210, vcc, 0x40000, v210
	s_nop 1
	v_addc_co_u32_e32 v211, vcc, 0, v211, vcc
	flat_load_dwordx4 v[210:213], v[210:211]
.Lskw_9:
	s_waitcnt vmcnt(0) lgkmcnt(0)
	v_lshlrev_b32_e32 v180, 16, v176
	v_and_b32_e32 v181, 0xffff0000, v176
	v_lshlrev_b32_e32 v176, 16, v177
	v_and_b32_e32 v177, 0xffff0000, v177
	v_lshlrev_b32_e32 v203, 16, v178
	v_and_b32_e32 v205, 0xffff0000, v178
	v_lshlrev_b32_e32 v178, 16, v179
	v_and_b32_e32 v179, 0xffff0000, v179
	v_pk_add_f32 v[182:183], v[30:31], v[176:177]
	v_pk_add_f32 v[180:181], v[28:29], v[180:181]
	v_pk_add_f32 v[178:179], v[26:27], v[178:179]
	v_add_f32_e32 v176, v24, v203
	v_add_f32_e32 v177, v25, v205
	s_cmp_lt_i32 s30, 2
	s_cbranch_scc1 .LBB0_1511
	v_lshlrev_b32_e32 v203, 16, v238
	v_and_b32_e32 v205, 0xffff0000, v238
	v_lshlrev_b32_e32 v238, 16, v239
	v_and_b32_e32 v239, 0xffff0000, v239
	v_pk_add_f32 v[182:183], v[182:183], v[238:239]
	v_add_f32_e32 v180, v180, v203
	v_add_f32_e32 v181, v181, v205
	v_lshlrev_b32_e32 v203, 16, v240
	v_and_b32_e32 v205, 0xffff0000, v240
	v_lshlrev_b32_e32 v238, 16, v241
	v_and_b32_e32 v239, 0xffff0000, v241
	v_pk_add_f32 v[178:179], v[178:179], v[238:239]
	v_add_f32_e32 v176, v176, v203
	v_add_f32_e32 v177, v177, v205
	s_cmp_lt_i32 s30, 3
	s_cbranch_scc1 .LBB0_1511
	v_lshlrev_b32_e32 v238, 16, v210
	v_and_b32_e32 v239, 0xffff0000, v210
	v_lshlrev_b32_e32 v210, 16, v211
	v_and_b32_e32 v211, 0xffff0000, v211
	v_pk_add_f32 v[182:183], v[182:183], v[210:211]
	v_lshlrev_b32_e32 v210, 16, v212
	v_and_b32_e32 v211, 0xffff0000, v212
	v_lshlrev_b32_e32 v212, 16, v213
	v_and_b32_e32 v213, 0xffff0000, v213
	v_pk_add_f32 v[180:181], v[180:181], v[238:239]
	v_pk_add_f32 v[178:179], v[178:179], v[212:213]
	v_pk_add_f32 v[176:177], v[176:177], v[210:211]

.LBB0_1518:
	v_ashrrev_i32_e32 v205, 31, v204
	v_lshlrev_b64 v[160:161], 12, v[204:205]
	v_lshl_add_u64 v[176:177], s[10:11], 0, v[160:161]
	v_lshl_add_u64 v[178:179], v[200:201], 2, v[176:177]
	global_load_dwordx4 v[164:167], v[178:179], off offset:16
	global_load_dwordx4 v[160:163], v[178:179], off
	v_mov_b64_e32 v[174:175], v[54:55]
	v_mov_b64_e32 v[170:171], v[50:51]
	s_and_b64 vcc, exec, s[84:85]
	v_mov_b64_e32 v[172:173], v[52:53]
	v_mov_b64_e32 v[168:169], v[48:49]
	s_cbranch_vccnz .LBB0_1523
	v_readlane_b32 s88, v242, 34
	v_readlane_b32 s89, v242, 35
	v_lshlrev_b32_e32 v180, 2, v194
	v_mov_b32_e32 v181, v185
	s_cmp_lt_i32 s30, 2
	v_lshl_add_u64 v[182:183], s[88:89], 0, v[180:181]
	flat_load_dwordx4 v[168:171], v[182:183]
	s_cbranch_scc1 .Lskw_10
	v_add_co_u32_e32 v182, vcc, 0x20000, v182
	s_nop 1
	v_addc_co_u32_e32 v183, vcc, 0, v183, vcc
	flat_load_dwordx4 v[206:209], v[182:183]
	s_cmp_lt_i32 s30, 3
	s_cbranch_scc1 .Lskw_10
	v_mov_b32_e32 v181, v185
	v_lshl_add_u64 v[180:181], s[88:89], 0, v[180:181]
	v_add_co_u32_e32 v180, vcc, 0x40000, v180
	s_nop 1
	v_addc_co_u32_e32 v181, vcc, 0, v181, vcc
	flat_load_dwordx4 v[180:183], v[180:181]
.Lskw_10:
	s_waitcnt vmcnt(0) lgkmcnt(0)
	v_lshlrev_b32_e32 v172, 16, v168
	v_and_b32_e32 v173, 0xffff0000, v168
	v_lshlrev_b32_e32 v168, 16, v169
	v_and_b32_e32 v169, 0xffff0000, v169
	v_lshlrev_b32_e32 v210, 16, v170
	v_and_b32_e32 v211, 0xffff0000, v170
	v_lshlrev_b32_e32 v170, 16, v171
	v_and_b32_e32 v171, 0xffff0000, v171
	v_pk_add_f32 v[174:175], v[54:55], v[168:169]
	v_pk_add_f32 v[172:173], v[52:53], v[172:173]
	v_pk_add_f32 v[170:171], v[50:51], v[170:171]
	v_pk_add_f32 v[168:169], v[48:49], v[210:211]
	s_cmp_lt_i32 s30, 2
	s_cbranch_scc1 .LBB0_1523
	v_lshlrev_b32_e32 v210, 16, v206
	v_and_b32_e32 v211, 0xffff0000, v206
	v_lshlrev_b32_e32 v206, 16, v207
	v_and_b32_e32 v207, 0xffff0000, v207
	v_pk_add_f32 v[174:175], v[174:175], v[206:207]
	v_pk_add_f32 v[172:173], v[172:173], v[210:211]
	v_lshlrev_b32_e32 v210, 16, v208
	v_and_b32_e32 v211, 0xffff0000, v208
	v_lshlrev_b32_e32 v206, 16, v209
	v_and_b32_e32 v207, 0xffff0000, v209
	v_pk_add_f32 v[170:171], v[170:171], v[206:207]
	v_pk_add_f32 v[168:169], v[168:169], v[210:211]
	s_cmp_lt_i32 s30, 3
	s_cbranch_scc1 .LBB0_1523
	v_lshlrev_b32_e32 v206, 16, v180
	v_and_b32_e32 v207, 0xffff0000, v180
	v_lshlrev_b32_e32 v180, 16, v181
	v_and_b32_e32 v181, 0xffff0000, v181
	v_pk_add_f32 v[174:175], v[174:175], v[180:181]
	v_lshlrev_b32_e32 v180, 16, v182
	v_and_b32_e32 v181, 0xffff0000, v182
	v_lshlrev_b32_e32 v182, 16, v183
	v_and_b32_e32 v183, 0xffff0000, v183
	v_pk_add_f32 v[172:173], v[172:173], v[206:207]
	v_pk_add_f32 v[170:171], v[170:171], v[182:183]
	v_pk_add_f32 v[168:169], v[168:169], v[180:181]

.LBB0_1525:
	v_lshl_add_u64 v[208:209], v[200:201], 2, v[176:177]
	global_load_dwordx4 v[168:171], v[208:209], off offset:528
	global_load_dwordx4 v[172:175], v[208:209], off offset:512
	v_mov_b64_e32 v[182:183], v[22:23]
	v_mov_b64_e32 v[178:179], v[18:19]
	s_and_b64 vcc, exec, s[84:85]
	v_mov_b64_e32 v[180:181], v[20:21]
	v_mov_b64_e32 v[176:177], v[16:17]
	s_cbranch_vccnz .LBB0_1530
	v_readlane_b32 s88, v242, 36
	v_readlane_b32 s89, v242, 37
	v_lshlrev_b32_e32 v210, 2, v194
	v_mov_b32_e32 v211, v185
	s_cmp_lt_i32 s30, 2
	v_lshl_add_u64 v[212:213], s[88:89], 0, v[210:211]
	flat_load_dwordx4 v[176:179], v[212:213]
	s_cbranch_scc1 .Lskw_11
	v_add_co_u32_e32 v212, vcc, 0x20000, v212
	s_nop 1
	v_addc_co_u32_e32 v213, vcc, 0, v213, vcc
	flat_load_dwordx4 v[238:241], v[212:213]
	s_cmp_lt_i32 s30, 3
	s_cbranch_scc1 .Lskw_11
	v_mov_b32_e32 v211, v185
	v_lshl_add_u64 v[210:211], s[88:89], 0, v[210:211]
	v_add_co_u32_e32 v210, vcc, 0x40000, v210
	s_nop 1
	v_addc_co_u32_e32 v211, vcc, 0, v211, vcc
	flat_load_dwordx4 v[210:213], v[210:211]
.Lskw_11:
	s_waitcnt vmcnt(0) lgkmcnt(0)
	v_lshlrev_b32_e32 v180, 16, v176
	v_and_b32_e32 v181, 0xffff0000, v176
	v_lshlrev_b32_e32 v176, 16, v177
	v_and_b32_e32 v177, 0xffff0000, v177
	v_lshlrev_b32_e32 v203, 16, v178
	v_and_b32_e32 v205, 0xffff0000, v178
	v_lshlrev_b32_e32 v178, 16, v179
	v_and_b32_e32 v179, 0xffff0000, v179
	v_pk_add_f32 v[182:183], v[22:23], v[176:177]
	v_pk_add_f32 v[180:181], v[20:21], v[180:181]
	v_pk_add_f32 v[178:179], v[18:19], v[178:179]
	v_add_f32_e32 v176, v16, v203
	v_add_f32_e32 v177, v17, v205
	s_cmp_lt_i32 s30, 2
	s_cbranch_scc1 .LBB0_1530
	v_lshlrev_b32_e32 v203, 16, v238
	v_and_b32_e32 v205, 0xffff0000, v238
	v_lshlrev_b32_e32 v238, 16, v239
	v_and_b32_e32 v239, 0xffff0000, v239
	v_pk_add_f32 v[182:183], v[182:183], v[238:239]
	v_add_f32_e32 v180, v180, v203
	v_add_f32_e32 v181, v181, v205
	v_lshlrev_b32_e32 v203, 16, v240
	v_and_b32_e32 v205, 0xffff0000, v240
	v_lshlrev_b32_e32 v238, 16, v241
	v_and_b32_e32 v239, 0xffff0000, v241
	v_pk_add_f32 v[178:179], v[178:179], v[238:239]
	v_add_f32_e32 v176, v176, v203
	v_add_f32_e32 v177, v177, v205
	s_cmp_lt_i32 s30, 3
	s_cbranch_scc1 .LBB0_1530
	v_lshlrev_b32_e32 v238, 16, v210
	v_and_b32_e32 v239, 0xffff0000, v210
	v_lshlrev_b32_e32 v210, 16, v211
	v_and_b32_e32 v211, 0xffff0000, v211
	v_pk_add_f32 v[182:183], v[182:183], v[210:211]
	v_lshlrev_b32_e32 v210, 16, v212
	v_and_b32_e32 v211, 0xffff0000, v212
	v_lshlrev_b32_e32 v212, 16, v213
	v_and_b32_e32 v213, 0xffff0000, v213
	v_pk_add_f32 v[180:181], v[180:181], v[238:239]
	v_pk_add_f32 v[178:179], v[178:179], v[212:213]
	v_pk_add_f32 v[176:177], v[176:177], v[210:211]

.LBB0_1537:
	v_ashrrev_i32_e32 v205, 31, v204
	v_lshlrev_b64 v[160:161], 12, v[204:205]
	v_lshl_add_u64 v[176:177], s[10:11], 0, v[160:161]
	v_lshl_add_u64 v[178:179], v[200:201], 2, v[176:177]
	global_load_dwordx4 v[164:167], v[178:179], off offset:16
	global_load_dwordx4 v[160:163], v[178:179], off
	v_mov_b64_e32 v[174:175], v[46:47]
	v_mov_b64_e32 v[170:171], v[42:43]
	s_and_b64 vcc, exec, s[84:85]
	v_mov_b64_e32 v[172:173], v[44:45]
	v_mov_b64_e32 v[168:169], v[40:41]
	s_cbranch_vccnz .LBB0_1542
	v_readlane_b32 s88, v242, 38
	v_readlane_b32 s89, v242, 39
	v_lshlrev_b32_e32 v180, 2, v194
	v_mov_b32_e32 v181, v185
	s_cmp_lt_i32 s30, 2
	v_lshl_add_u64 v[182:183], s[88:89], 0, v[180:181]
	flat_load_dwordx4 v[168:171], v[182:183]
	s_cbranch_scc1 .Lskw_12
	v_add_co_u32_e32 v182, vcc, 0x20000, v182
	s_nop 1
	v_addc_co_u32_e32 v183, vcc, 0, v183, vcc
	flat_load_dwordx4 v[206:209], v[182:183]
	s_cmp_lt_i32 s30, 3
	s_cbranch_scc1 .Lskw_12
	v_mov_b32_e32 v181, v185
	v_lshl_add_u64 v[180:181], s[88:89], 0, v[180:181]
	v_add_co_u32_e32 v180, vcc, 0x40000, v180
	s_nop 1
	v_addc_co_u32_e32 v181, vcc, 0, v181, vcc
	flat_load_dwordx4 v[180:183], v[180:181]
.Lskw_12:
	s_waitcnt vmcnt(0) lgkmcnt(0)
	v_lshlrev_b32_e32 v172, 16, v168
	v_and_b32_e32 v173, 0xffff0000, v168
	v_lshlrev_b32_e32 v168, 16, v169
	v_and_b32_e32 v169, 0xffff0000, v169
	v_lshlrev_b32_e32 v210, 16, v170
	v_and_b32_e32 v211, 0xffff0000, v170
	v_lshlrev_b32_e32 v170, 16, v171
	v_and_b32_e32 v171, 0xffff0000, v171
	v_pk_add_f32 v[174:175], v[46:47], v[168:169]
	v_pk_add_f32 v[172:173], v[44:45], v[172:173]
	v_pk_add_f32 v[170:171], v[42:43], v[170:171]
	v_pk_add_f32 v[168:169], v[40:41], v[210:211]
	s_cmp_lt_i32 s30, 2
	s_cbranch_scc1 .LBB0_1542
	v_lshlrev_b32_e32 v210, 16, v206
	v_and_b32_e32 v211, 0xffff0000, v206
	v_lshlrev_b32_e32 v206, 16, v207
	v_and_b32_e32 v207, 0xffff0000, v207
	v_pk_add_f32 v[174:175], v[174:175], v[206:207]
	v_pk_add_f32 v[172:173], v[172:173], v[210:211]
	v_lshlrev_b32_e32 v210, 16, v208
	v_and_b32_e32 v211, 0xffff0000, v208
	v_lshlrev_b32_e32 v206, 16, v209
	v_and_b32_e32 v207, 0xffff0000, v209
	v_pk_add_f32 v[170:171], v[170:171], v[206:207]
	v_pk_add_f32 v[168:169], v[168:169], v[210:211]
	s_cmp_lt_i32 s30, 3
	s_cbranch_scc1 .LBB0_1542
	v_lshlrev_b32_e32 v206, 16, v180
	v_and_b32_e32 v207, 0xffff0000, v180
	v_lshlrev_b32_e32 v180, 16, v181
	v_and_b32_e32 v181, 0xffff0000, v181
	v_pk_add_f32 v[174:175], v[174:175], v[180:181]
	v_lshlrev_b32_e32 v180, 16, v182
	v_and_b32_e32 v181, 0xffff0000, v182
	v_lshlrev_b32_e32 v182, 16, v183
	v_and_b32_e32 v183, 0xffff0000, v183
	v_pk_add_f32 v[172:173], v[172:173], v[206:207]
	v_pk_add_f32 v[170:171], v[170:171], v[182:183]
	v_pk_add_f32 v[168:169], v[168:169], v[180:181]

.LBB0_1544:
	v_lshl_add_u64 v[208:209], v[200:201], 2, v[176:177]
	global_load_dwordx4 v[168:171], v[208:209], off offset:528
	global_load_dwordx4 v[172:175], v[208:209], off offset:512
	v_mov_b64_e32 v[182:183], v[14:15]
	v_mov_b64_e32 v[178:179], v[10:11]
	s_and_b64 vcc, exec, s[84:85]
	v_mov_b64_e32 v[180:181], v[12:13]
	v_mov_b64_e32 v[176:177], v[8:9]
	s_cbranch_vccnz .LBB0_1549
	v_readlane_b32 s88, v242, 40
	v_readlane_b32 s89, v242, 41
	v_lshlrev_b32_e32 v210, 2, v194
	v_mov_b32_e32 v211, v185
	s_cmp_lt_i32 s30, 2
	v_lshl_add_u64 v[212:213], s[88:89], 0, v[210:211]
	flat_load_dwordx4 v[176:179], v[212:213]
	s_cbranch_scc1 .Lskw_13
	v_add_co_u32_e32 v212, vcc, 0x20000, v212
	s_nop 1
	v_addc_co_u32_e32 v213, vcc, 0, v213, vcc
	flat_load_dwordx4 v[238:241], v[212:213]
	s_cmp_lt_i32 s30, 3
	s_cbranch_scc1 .Lskw_13
	v_mov_b32_e32 v211, v185
	v_lshl_add_u64 v[210:211], s[88:89], 0, v[210:211]
	v_add_co_u32_e32 v210, vcc, 0x40000, v210
	s_nop 1
	v_addc_co_u32_e32 v211, vcc, 0, v211, vcc
	flat_load_dwordx4 v[210:213], v[210:211]
.Lskw_13:
	s_waitcnt vmcnt(0) lgkmcnt(0)
	v_lshlrev_b32_e32 v180, 16, v176
	v_and_b32_e32 v181, 0xffff0000, v176
	v_lshlrev_b32_e32 v176, 16, v177
	v_and_b32_e32 v177, 0xffff0000, v177
	v_lshlrev_b32_e32 v203, 16, v178
	v_and_b32_e32 v205, 0xffff0000, v178
	v_lshlrev_b32_e32 v178, 16, v179
	v_and_b32_e32 v179, 0xffff0000, v179
	v_pk_add_f32 v[182:183], v[14:15], v[176:177]
	v_pk_add_f32 v[180:181], v[12:13], v[180:181]
	v_pk_add_f32 v[178:179], v[10:11], v[178:179]
	v_add_f32_e32 v176, v8, v203
	v_add_f32_e32 v177, v9, v205
	s_cmp_lt_i32 s30, 2
	s_cbranch_scc1 .LBB0_1549
	v_lshlrev_b32_e32 v203, 16, v238
	v_and_b32_e32 v205, 0xffff0000, v238
	v_lshlrev_b32_e32 v238, 16, v239
	v_and_b32_e32 v239, 0xffff0000, v239
	v_pk_add_f32 v[182:183], v[182:183], v[238:239]
	v_add_f32_e32 v180, v180, v203
	v_add_f32_e32 v181, v181, v205
	v_lshlrev_b32_e32 v203, 16, v240
	v_and_b32_e32 v205, 0xffff0000, v240
	v_lshlrev_b32_e32 v238, 16, v241
	v_and_b32_e32 v239, 0xffff0000, v241
	v_pk_add_f32 v[178:179], v[178:179], v[238:239]
	v_add_f32_e32 v176, v176, v203
	v_add_f32_e32 v177, v177, v205
	s_cmp_lt_i32 s30, 3
	s_cbranch_scc1 .LBB0_1549
	v_lshlrev_b32_e32 v238, 16, v210
	v_and_b32_e32 v239, 0xffff0000, v210
	v_lshlrev_b32_e32 v210, 16, v211
	v_and_b32_e32 v211, 0xffff0000, v211
	v_pk_add_f32 v[182:183], v[182:183], v[210:211]
	v_lshlrev_b32_e32 v210, 16, v212
	v_and_b32_e32 v211, 0xffff0000, v212
	v_lshlrev_b32_e32 v212, 16, v213
	v_and_b32_e32 v213, 0xffff0000, v213
	v_pk_add_f32 v[180:181], v[180:181], v[238:239]
	v_pk_add_f32 v[178:179], v[178:179], v[212:213]
	v_pk_add_f32 v[176:177], v[176:177], v[210:211]
